# k16a: k13 + attention K-fragment waits merged per d-step (6 fewer s_waitcnt per tile step)
# baseline (speedup 1.0000x reference)
.LBB0_299:
	v_add_u32_e32 v193, s25, v203
	s_waitcnt lgkmcnt(4)
	v_mfma_f32_32x32x16_bf16 v[64:79], v[160:163], v[98:101], v[174:189]
	v_exp_f32_e32 v32, v32
	v_exp_f32_e32 v33, v33
	v_mfma_f32_32x32x16_bf16 v[80:95], v[164:167], v[98:101], v[174:189]
	v_add_u32_e32 v214, v193, v207
	ds_read_b128 v[160:163], v214 offset:6144
	ds_read_b128 v[164:167], v214 offset:6656
	v_exp_f32_e32 v34, v34
	v_exp_f32_e32 v35, v35
	s_waitcnt lgkmcnt(4)
	v_mfma_f32_32x32x16_bf16 v[64:79], v[224:227], v[102:105], v[64:79]
	v_exp_f32_e32 v36, v36
	v_exp_f32_e32 v37, v37
	v_mfma_f32_32x32x16_bf16 v[80:95], v[228:231], v[102:105], v[80:95]
	v_add_u32_e32 v214, v193, v209
	ds_read_b128 v[224:227], v214 offset:10240
	ds_read_b128 v[228:231], v214 offset:10752
	v_exp_f32_e32 v38, v38
	v_exp_f32_e32 v39, v39
	s_waitcnt lgkmcnt(4)
	v_mfma_f32_32x32x16_bf16 v[64:79], v[242:245], v[106:109], v[64:79]
	v_exp_f32_e32 v40, v40
	v_exp_f32_e32 v41, v41
	v_mfma_f32_32x32x16_bf16 v[80:95], v[246:249], v[106:109], v[80:95]
	v_add_u32_e32 v214, v193, v208
	ds_read_b128 v[242:245], v214 offset:8192
	ds_read_b128 v[246:249], v214 offset:8704
	v_add_u32_e32 v213, s11, v218
	v_exp_f32_e32 v42, v42
	v_exp_f32_e32 v43, v43
	s_waitcnt lgkmcnt(4)
	v_mfma_f32_32x32x16_bf16 v[64:79], v[160:163], v[110:113], v[64:79]
	v_exp_f32_e32 v44, v44
	v_exp_f32_e32 v45, v45
	v_mfma_f32_32x32x16_bf16 v[80:95], v[164:167], v[110:113], v[80:95]
	ds_read_b64_tr_b16 v[168:169], v213 offset:12288
	ds_read_b64_tr_b16 v[170:171], v213 offset:13824
	v_exp_f32_e32 v46, v46
	v_exp_f32_e32 v47, v47
	s_waitcnt lgkmcnt(2)
	v_mfma_f32_32x32x16_bf16 v[64:79], v[242:245], v[114:117], v[64:79]
	ds_read_b64_tr_b16 v[250:251], v213 offset:12352
	ds_read_b64_tr_b16 v[252:253], v213 offset:13888
	v_cvt_pk_bf16_f32 v242, v32, v33
	v_cvt_pk_bf16_f32 v243, v34, v35
	v_exp_f32_e32 v48, v48
	v_exp_f32_e32 v49, v49
	v_mfma_f32_32x32x16_bf16 v[80:95], v[246:249], v[114:117], v[80:95]
	ds_read_b64_tr_b16 v[160:161], v213 offset:15360
	ds_read_b64_tr_b16 v[162:163], v213 offset:16896
	v_cvt_pk_bf16_f32 v244, v36, v37
	v_cvt_pk_bf16_f32 v245, v38, v39
	v_exp_f32_e32 v50, v50
	v_exp_f32_e32 v51, v51
	s_waitcnt lgkmcnt(8)
	v_mfma_f32_32x32x16_bf16 v[64:79], v[224:227], v[118:121], v[64:79]
	ds_read_b64_tr_b16 v[164:165], v213 offset:15424
	ds_read_b64_tr_b16 v[166:167], v213 offset:16960
	v_cvt_pk_bf16_f32 v224, v40, v41
	v_cvt_pk_bf16_f32 v225, v42, v43
	v_exp_f32_e32 v52, v52
	v_exp_f32_e32 v53, v53
	v_mfma_f32_32x32x16_bf16 v[80:95], v[228:231], v[118:121], v[80:95]
	ds_read_b64_tr_b16 v[228:229], v213 offset:18432
	ds_read_b64_tr_b16 v[230:231], v213 offset:19968
	v_cvt_pk_bf16_f32 v226, v44, v45
	v_cvt_pk_bf16_f32 v227, v46, v47
	v_exp_f32_e32 v54, v54
	v_exp_f32_e32 v55, v55
	s_waitcnt lgkmcnt(8)
	v_mfma_f32_32x32x16_bf16 v[16:31], v[242:245], v[168:171], v[16:31]
	ds_read_b64_tr_b16 v[168:169], v213 offset:18496
	ds_read_b64_tr_b16 v[170:171], v213 offset:20032
	v_cvt_pk_bf16_f32 v246, v48, v49
	v_exp_f32_e32 v56, v56
	v_exp_f32_e32 v57, v57
	v_add_f32_e32 v216, v32, v34
	v_add_f32_e32 v217, v33, v35
	s_waitcnt lgkmcnt(8)
	v_mfma_f32_32x32x16_bf16 v[0:15], v[242:245], v[250:253], v[0:15]
	ds_read_b64_tr_b16 v[250:251], v213 offset:21504
	ds_read_b64_tr_b16 v[252:253], v213 offset:23040
	v_cvt_pk_bf16_f32 v247, v50, v51
	v_exp_f32_e32 v58, v58
	v_exp_f32_e32 v59, v59
	v_add_f32_e32 v216, v216, v36
	v_add_f32_e32 v217, v217, v37
	s_waitcnt lgkmcnt(8)
	v_mfma_f32_32x32x16_bf16 v[16:31], v[224:227], v[160:163], v[16:31]
	ds_read_b64_tr_b16 v[160:161], v213 offset:21568
	ds_read_b64_tr_b16 v[162:163], v213 offset:23104
	v_cvt_pk_bf16_f32 v248, v52, v53
	v_exp_f32_e32 v60, v60
	v_exp_f32_e32 v61, v61
	v_add_f32_e32 v216, v216, v38
	v_add_f32_e32 v217, v217, v39
	v_add_u32_e32 v215, s27, v97
	s_waitcnt vmcnt(5)
	ds_write_b128 v215, v[122:125]
	s_cmp_eq_u64 s[42:43], 0
	s_cbranch_scc1 .Lat_w1_1_body
	v_add_u32_e32 v215, s27, v147
	s_waitcnt vmcnt(4)
	ds_write_b128 v215, v[126:129]

.LBB0_309:
	v_add3_u32 v212, s27, v201, v202
	s_waitcnt lgkmcnt(4)
	v_mfma_f32_32x32x16_bf16 v[32:47], v[160:163], v[98:101], v[174:189]
	v_exp_f32_e32 v64, v64
	v_exp_f32_e32 v65, v65
	v_mfma_f32_32x32x16_bf16 v[48:63], v[164:167], v[98:101], v[174:189]
	v_add_u32_e32 v214, v212, v207
	ds_read_b128 v[160:163], v214 offset:6144
	ds_read_b128 v[164:167], v214 offset:6656
	v_exp_f32_e32 v66, v66
	v_exp_f32_e32 v67, v67
	s_waitcnt lgkmcnt(4)
	v_mfma_f32_32x32x16_bf16 v[32:47], v[224:227], v[102:105], v[32:47]
	v_exp_f32_e32 v68, v68
	v_exp_f32_e32 v69, v69
	v_mfma_f32_32x32x16_bf16 v[48:63], v[228:231], v[102:105], v[48:63]
	v_add_u32_e32 v214, v212, v209
	ds_read_b128 v[224:227], v214 offset:10240
	ds_read_b128 v[228:231], v214 offset:10752
	v_exp_f32_e32 v70, v70
	v_exp_f32_e32 v71, v71
	s_waitcnt lgkmcnt(4)
	v_mfma_f32_32x32x16_bf16 v[32:47], v[242:245], v[106:109], v[32:47]
	v_exp_f32_e32 v72, v72
	v_exp_f32_e32 v73, v73
	v_mfma_f32_32x32x16_bf16 v[48:63], v[246:249], v[106:109], v[48:63]
	v_add_u32_e32 v214, v212, v208
	ds_read_b128 v[242:245], v214 offset:8192
	ds_read_b128 v[246:249], v214 offset:8704
	v_add_u32_e32 v213, s25, v218
	v_exp_f32_e32 v74, v74
	v_exp_f32_e32 v75, v75
	s_waitcnt lgkmcnt(4)
	v_mfma_f32_32x32x16_bf16 v[32:47], v[160:163], v[110:113], v[32:47]
	v_exp_f32_e32 v76, v76
	v_exp_f32_e32 v77, v77
	v_mfma_f32_32x32x16_bf16 v[48:63], v[164:167], v[110:113], v[48:63]
	ds_read_b64_tr_b16 v[168:169], v213 offset:12288
	ds_read_b64_tr_b16 v[170:171], v213 offset:13824
	v_exp_f32_e32 v78, v78
	v_exp_f32_e32 v79, v79
	s_waitcnt lgkmcnt(2)
	v_mfma_f32_32x32x16_bf16 v[32:47], v[242:245], v[114:117], v[32:47]
	ds_read_b64_tr_b16 v[250:251], v213 offset:12352
	ds_read_b64_tr_b16 v[252:253], v213 offset:13888
	v_cvt_pk_bf16_f32 v242, v64, v65
	v_cvt_pk_bf16_f32 v243, v66, v67
	v_exp_f32_e32 v80, v80
	v_exp_f32_e32 v81, v81
	v_mfma_f32_32x32x16_bf16 v[48:63], v[246:249], v[114:117], v[48:63]
	ds_read_b64_tr_b16 v[160:161], v213 offset:15360
	ds_read_b64_tr_b16 v[162:163], v213 offset:16896
	v_cvt_pk_bf16_f32 v244, v68, v69
	v_cvt_pk_bf16_f32 v245, v70, v71
	v_exp_f32_e32 v82, v82
	v_exp_f32_e32 v83, v83
	s_waitcnt lgkmcnt(8)
	v_mfma_f32_32x32x16_bf16 v[32:47], v[224:227], v[118:121], v[32:47]
	ds_read_b64_tr_b16 v[164:165], v213 offset:15424
	ds_read_b64_tr_b16 v[166:167], v213 offset:16960
	v_cvt_pk_bf16_f32 v224, v72, v73
	v_cvt_pk_bf16_f32 v225, v74, v75
	v_exp_f32_e32 v84, v84
	v_exp_f32_e32 v85, v85
	v_mfma_f32_32x32x16_bf16 v[48:63], v[228:231], v[118:121], v[48:63]
	ds_read_b64_tr_b16 v[228:229], v213 offset:18432
	ds_read_b64_tr_b16 v[230:231], v213 offset:19968
	v_cvt_pk_bf16_f32 v226, v76, v77
	v_cvt_pk_bf16_f32 v227, v78, v79
	v_exp_f32_e32 v86, v86
	v_exp_f32_e32 v87, v87
	s_waitcnt lgkmcnt(8)
	v_mfma_f32_32x32x16_bf16 v[16:31], v[242:245], v[168:171], v[16:31]
	ds_read_b64_tr_b16 v[168:169], v213 offset:18496
	ds_read_b64_tr_b16 v[170:171], v213 offset:20032
	v_cvt_pk_bf16_f32 v246, v80, v81
	v_exp_f32_e32 v88, v88
	v_exp_f32_e32 v89, v89
	v_add_f32_e32 v216, v64, v66
	v_add_f32_e32 v217, v65, v67
	s_waitcnt lgkmcnt(8)
	v_mfma_f32_32x32x16_bf16 v[0:15], v[242:245], v[250:253], v[0:15]
	ds_read_b64_tr_b16 v[250:251], v213 offset:21504
	ds_read_b64_tr_b16 v[252:253], v213 offset:23040
	v_cvt_pk_bf16_f32 v247, v82, v83
	v_exp_f32_e32 v90, v90
	v_exp_f32_e32 v91, v91
	v_add_f32_e32 v216, v216, v68
	v_add_f32_e32 v217, v217, v69
	s_waitcnt lgkmcnt(8)
	v_mfma_f32_32x32x16_bf16 v[16:31], v[224:227], v[160:163], v[16:31]
	ds_read_b64_tr_b16 v[160:161], v213 offset:21568
	ds_read_b64_tr_b16 v[162:163], v213 offset:23104
	v_cvt_pk_bf16_f32 v248, v84, v85
	v_exp_f32_e32 v92, v92
	v_exp_f32_e32 v93, v93
	v_add_f32_e32 v216, v216, v70
	v_add_f32_e32 v217, v217, v71
	v_add_u32_e32 v215, s11, v97
	s_waitcnt vmcnt(5)
	ds_write_b128 v215, v[134:137]
	s_cmp_eq_u64 s[42:43], 0
	s_cbranch_scc1 .Lat_w1_2_body
	v_add_u32_e32 v215, s11, v147
	s_waitcnt vmcnt(4)
	ds_write_b128 v215, v[138:141]
